# GEMM K-loop static priority raise on the other half (waves 0-3), per-block flips removed
# baseline (speedup 1.0000x reference)
.LBB0_1022:
	v_readfirstlane_b32 s101, v135
	s_nop 1
	s_lshr_b32 s101, s101, 6
	s_cmp_lt_u32 s101, 4
	s_mov_b32 s101, 0
	s_cbranch_scc0 .Lprio_done
	s_setprio 1
